# v18 + layer-0 up-GEMM epilogue (conv+gelu+gate) re-synthesised with packed f32 (v_pk_mul/fma_f32), bit-identical per element
# speedup vs baseline: 1.0040x; 1.0040x over previous
; __device__ __forceinline__ unsigned cvt_pk_bf16(float lo, float hi) { unsigned r; asm volatile("v_cvt_pk_bf16_f32 %0, %1, %2" : "=v"(r) : "v"(lo), "v"(hi)); return r; }
; __device__ __forceinline__ float gelu_tanh(float x) { const float u = x * (1.5957691216057308f + 0.0713548162726009f * x * x); return x * sigmoid_f(u); }
;     __device__ __forceinline__ static float dpp_up(float old, float src) { return __builtin_bit_cast(float, __builtin_amdgcn_update_dpp(__builtin_bit_cast(int, old), __builtin_bit_cast(int, src), 0x111, 0xf, 0xf, false)); }
;     __device__ __forceinline__ void operator()(const f32x4 (&acc)[2][2][4][2], const Unit& u, int wr, int wc, int fr, int fq) const {
;     ...
;                 const f32x4 a0 = acc[ai][0][0][n] * rs[ai][0], a1 = acc[ai][0][1][n] * rs[ai][1], a2 = acc[ai][0][2][n] * rs[ai][2], a3 = acc[ai][0][3][n] * rs[ai][3];
;                 f32x4 o0, o1, o2, o3;
; #pragma unroll
;                 for (int j = 0; j < 4; ++j) { const float p3 = dpp_up(h3[j], a3[j]), p2 = dpp_up(h2[j], a2[j]);
;                     o0[j] = gelu_tanh(bb[j] + w0[j] * p2 + w1[j] * p3 + w2[j] * a0[j]) * (acc[ai][1][0][n][j] * rs[ai][0]);
;                     o1[j] = gelu_tanh(bb[j] + w0[j] * p3 + w1[j] * a0[j] + w2[j] * a1[j]) * (acc[ai][1][1][n][j] * rs[ai][1]);
;                     o2[j] = gelu_tanh(bb[j] + w0[j] * a0[j] + w1[j] * a1[j] + w2[j] * a2[j]) * (acc[ai][1][2][n][j] * rs[ai][2]);
;                     o3[j] = gelu_tanh(bb[j] + w0[j] * a1[j] + w1[j] * a2[j] + w2[j] * a3[j]) * (acc[ai][1][3][n][j] * rs[ai][3]); }
;                 pk[0][n].x = cvt_pk_bf16(o0[0], o0[1]); pk[0][n].y = cvt_pk_bf16(o0[2], o0[3]); pk[1][n].x = cvt_pk_bf16(o1[0], o1[1]); pk[1][n].y = cvt_pk_bf16(o1[2], o1[3]);
;                 pk[2][n].x = cvt_pk_bf16(o2[0], o2[1]); pk[2][n].y = cvt_pk_bf16(o2[2], o2[3]); pk[3][n].x = cvt_pk_bf16(o3[0], o3[1]); pk[3][n].y = cvt_pk_bf16(o3[2], o3[3]);
.LBB0_407:
	v_fmamk_f32 v132, v160, 0x3a000000, v244
	v_rsq_f32_e32 v224, v132
	v_fmamk_f32 v132, v161, 0x3a000000, v244
	s_waitcnt vmcnt(1) lgkmcnt(1)
	v_mov_b32_dpp v172, v156 row_shr:1 row_mask:0xf bank_mask:0xf
	v_rsq_f32_e32 v222, v132
	v_mov_b32_e32 v225, v224
	s_waitcnt vmcnt(0) lgkmcnt(0)
	s_and_b32 s33, s52, 15
	s_cmp_lg_u32 s33, 0
	v_readlane_b32 s30, v249, 31
	s_nop 1
	s_cselect_b64 s[6:7], -1, 0
	v_readlane_b32 s31, v249, 32
	s_nop 1
	s_and_b64 s[6:7], s[30:31], s[6:7]
	s_and_b64 s[6:7], s[16:17], s[6:7]
	s_mul_hi_i32 s65, s52, 0x16000
	s_mul_i32 s68, s52, 0x16000
	s_and_b64 s[30:31], s[84:85], s[6:7]
	s_mov_b32 s36, 1.0
	s_mov_b32 s38, 0xbfb8aa3b
	s_mov_b32 s40, 0x3d922279
	s_mov_b32 s42, 0x3fcc422a
	v_mul_f32_e32 v215, v92, v224
	v_mul_f32_e32 v217, v124, v224
	v_mov_b32_e32 v245, v168
	s_nop 1
	v_mov_b32_dpp v245, v152 row_shr:1 row_mask:0xf bank_mask:0xf
	v_fma_f32 v248, v148, v172, v136
	v_fma_f32 v172, v140, v245, v248
	v_fma_f32 v248, v217, v144, v172
	v_mul_f32_e32 v172, 0x3d922279, v248
	v_fmaak_f32 v251, v248, v172, 0x3fcc422a
	v_mul_f32_e32 v172, v248, v251
	v_mul_f32_e32 v251, 0xbfb8aa3b, v172
	v_exp_f32_e32 v172, v251
	s_nop 0
	v_add_f32_e32 v251, 1.0, v172
	v_rcp_f32_e32 v172, v251
	s_nop 0
	v_mul_f32_e32 v251, v248, v172
	v_mul_f32_e32 v132, v215, v251
	v_mul_f32_e32 v172, v84, v222
	v_mul_f32_e32 v215, v116, v222
	v_fma_f32 v248, v148, v245, v136
	v_fma_f32 v245, v217, v140, v248
	v_fma_f32 v217, v215, v144, v245
	v_mul_f32_e32 v215, 0x3d922279, v217
	v_fmaak_f32 v245, v217, v215, 0x3fcc422a
	v_mul_f32_e32 v215, v217, v245
	v_mul_f32_e32 v245, 0xbfb8aa3b, v215
	v_exp_f32_e32 v215, v245
	s_nop 0
	v_add_f32_e32 v245, 1.0, v215
	v_rcp_f32_e32 v215, v245
	s_nop 0
	v_mul_f32_e32 v245, v217, v215
	v_mul_f32_e32 v133, v172, v245
	v_pk_mul_f32 v[208:209], v[68:69], v[214:215] op_sel_hi:[1,0]
	v_pk_mul_f32 v[160:161], v[116:117], v[222:223] op_sel_hi:[1,0]
	v_pk_fma_f32 v[218:219], v[160:161], v[148:149], v[136:137]
	v_pk_fma_f32 v[220:221], v[156:157], v[140:141], v[218:219]
	v_pk_fma_f32 v[218:219], v[152:153], v[144:145], v[220:221]
	v_pk_mul_f32 v[220:221], s[40:41], v[218:219] op_sel_hi:[0,1]
	v_pk_fma_f32 v[226:227], v[218:219], v[220:221], s[42:43] op_sel_hi:[1,1,0]
	v_pk_mul_f32 v[220:221], v[218:219], v[226:227]
	v_pk_mul_f32 v[226:227], s[38:39], v[220:221] op_sel_hi:[0,1]
	v_exp_f32_e32 v220, v226
	v_exp_f32_e32 v221, v227
	s_nop 0
	v_pk_add_f32 v[226:227], s[36:37], v[220:221] op_sel_hi:[0,1]
	v_rcp_f32_e32 v220, v226
	v_rcp_f32_e32 v221, v227
	s_nop 0
	v_pk_mul_f32 v[226:227], v[218:219], v[220:221]
	v_pk_mul_f32 v[218:219], v[208:209], v[226:227]
	v_cvt_pk_bf16_f32 v172, v218, v219
	v_pk_mul_f32 v[208:209], v[70:71], v[214:215] op_sel_hi:[1,0]
	v_pk_mul_f32 v[154:155], v[102:103], v[214:215] op_sel_hi:[1,0]
	v_pk_mul_f32 v[158:159], v[110:111], v[216:217] op_sel_hi:[1,0]
	v_pk_mul_f32 v[162:163], v[118:119], v[222:223] op_sel_hi:[1,0]
	v_pk_fma_f32 v[220:221], v[162:163], v[150:151], v[138:139]
	v_pk_fma_f32 v[226:227], v[158:159], v[142:143], v[220:221]
	v_pk_fma_f32 v[220:221], v[154:155], v[146:147], v[226:227]
	v_pk_mul_f32 v[226:227], s[40:41], v[220:221] op_sel_hi:[0,1]
	v_pk_fma_f32 v[228:229], v[220:221], v[226:227], s[42:43] op_sel_hi:[1,1,0]
	v_pk_mul_f32 v[226:227], v[220:221], v[228:229]
	v_pk_mul_f32 v[228:229], s[38:39], v[226:227] op_sel_hi:[0,1]
	v_exp_f32_e32 v226, v228
	v_exp_f32_e32 v227, v229
	s_nop 0
	v_pk_add_f32 v[228:229], s[36:37], v[226:227] op_sel_hi:[0,1]
	v_rcp_f32_e32 v226, v228
	v_rcp_f32_e32 v227, v229
	s_nop 0
	v_pk_mul_f32 v[228:229], v[220:221], v[226:227]
	v_pk_mul_f32 v[220:221], v[208:209], v[228:229]
	v_cvt_pk_bf16_f32 v215, v220, v221
	v_mul_f32_e32 v217, v93, v224
	v_mul_f32_e32 v245, v125, v224
	v_mov_b32_e32 v248, v169
	s_nop 1
	v_mov_b32_dpp v248, v153 row_shr:1 row_mask:0xf bank_mask:0xf
	v_mov_b32_e32 v251, v173
	s_nop 1
	v_mov_b32_dpp v251, v157 row_shr:1 row_mask:0xf bank_mask:0xf
	v_fma_f32 v173, v149, v251, v137
	v_fma_f32 v251, v141, v248, v173
	v_fma_f32 v173, v245, v145, v251
	v_mul_f32_e32 v245, 0x3d922279, v173
	v_fmaak_f32 v248, v173, v245, 0x3fcc422a
	v_mul_f32_e32 v245, v173, v248
	v_mul_f32_e32 v248, 0xbfb8aa3b, v245
	v_exp_f32_e32 v245, v248
	s_nop 0
	v_add_f32_e32 v248, 1.0, v245
	v_rcp_f32_e32 v245, v248
	s_nop 0
	v_mul_f32_e32 v248, v173, v245
	v_mul_f32_e32 v173, v217, v248
	v_mul_f32_e32 v217, v94, v224
	v_mul_f32_e32 v245, v126, v224
	v_mul_f32_e32 v248, v102, v214
	v_mov_b32_e32 v251, v170
	s_nop 1
	v_mov_b32_dpp v251, v248 row_shr:1 row_mask:0xf bank_mask:0xf
	v_mul_f32_e32 v248, v110, v216
	v_mov_b32_e32 v255, v174
	s_nop 1
	v_mov_b32_dpp v255, v248 row_shr:1 row_mask:0xf bank_mask:0xf
	v_fma_f32 v248, v150, v255, v138
	v_fma_f32 v255, v142, v251, v248
	v_fma_f32 v248, v245, v146, v255
	v_mul_f32_e32 v245, 0x3d922279, v248
	v_fmaak_f32 v251, v248, v245, 0x3fcc422a
	v_mul_f32_e32 v245, v248, v251
	v_mul_f32_e32 v251, 0xbfb8aa3b, v245
	v_exp_f32_e32 v245, v251
	s_nop 0
	v_add_f32_e32 v251, 1.0, v245
	v_rcp_f32_e32 v245, v251
	s_nop 0
	v_mul_f32_e32 v251, v248, v245
	v_mul_f32_e32 v245, v217, v251
	v_pk_mul_f32 v[208:209], v[76:77], v[216:217] op_sel_hi:[1,0]
	v_pk_mul_f32 v[164:165], v[124:125], v[224:225] op_sel_hi:[1,0]
	v_pk_fma_f32 v[220:221], v[164:165], v[148:149], v[136:137]
	v_pk_fma_f32 v[226:227], v[160:161], v[140:141], v[220:221]
	v_pk_fma_f32 v[220:221], v[156:157], v[144:145], v[226:227]
	v_pk_mul_f32 v[226:227], s[40:41], v[220:221] op_sel_hi:[0,1]
	v_pk_fma_f32 v[228:229], v[220:221], v[226:227], s[42:43] op_sel_hi:[1,1,0]
	v_pk_mul_f32 v[226:227], v[220:221], v[228:229]
; __device__ __forceinline__ unsigned cvt_pk_bf16(float lo, float hi) { unsigned r; asm volatile("v_cvt_pk_bf16_f32 %0, %1, %2" : "=v"(r) : "v"(lo), "v"(hi)); return r; }
; __device__ __forceinline__ void st16_wt(void* p, f32x4 v) { asm volatile("global_store_dwordx4 %0, %1, off sc1\n\ts_nop 1" :: "v"(p), "v"(v) : "memory"); }
; __device__ __forceinline__ float gelu_tanh(float x) { const float u = x * (1.5957691216057308f + 0.0713548162726009f * x * x); return x * sigmoid_f(u); }
;     __device__ __forceinline__ static float dpp_up(float old, float src) { return __builtin_bit_cast(float, __builtin_amdgcn_update_dpp(__builtin_bit_cast(int, old), __builtin_bit_cast(int, src), 0x111, 0xf, 0xf, false)); }
;     __device__ __forceinline__ void operator()(const f32x4 (&acc)[2][2][4][2], const Unit& u, int wr, int wc, int fr, int fq) const {
;     ...
;                 for (int j = 0; j < 4; ++j) { const float p3 = dpp_up(h3[j], a3[j]), p2 = dpp_up(h2[j], a2[j]);
;                     o0[j] = gelu_tanh(bb[j] + w0[j] * p2 + w1[j] * p3 + w2[j] * a0[j]) * (acc[ai][1][0][n][j] * rs[ai][0]);
;                     o1[j] = gelu_tanh(bb[j] + w0[j] * p3 + w1[j] * a0[j] + w2[j] * a1[j]) * (acc[ai][1][1][n][j] * rs[ai][1]);
;                     o2[j] = gelu_tanh(bb[j] + w0[j] * a0[j] + w1[j] * a1[j] + w2[j] * a2[j]) * (acc[ai][1][2][n][j] * rs[ai][2]);
;                     o3[j] = gelu_tanh(bb[j] + w0[j] * a1[j] + w1[j] * a2[j] + w2[j] * a3[j]) * (acc[ai][1][3][n][j] * rs[ai][3]); }
;                 pk[0][n].x = cvt_pk_bf16(o0[0], o0[1]); pk[0][n].y = cvt_pk_bf16(o0[2], o0[3]); pk[1][n].x = cvt_pk_bf16(o1[0], o1[1]); pk[1][n].y = cvt_pk_bf16(o1[2], o1[3]);
;                 pk[2][n].x = cvt_pk_bf16(o2[0], o2[1]); pk[2][n].y = cvt_pk_bf16(o2[2], o2[3]); pk[3][n].x = cvt_pk_bf16(o3[0], o3[1]); pk[3][n].y = cvt_pk_bf16(o3[2], o3[3]);
;                 if (pend && fr == 0) {
;                     st16_wt(PEND + (((size_t)u.pm * 2 + 0) * 2 + 0) * DFFC + c, a0); st16_wt(PEND + (((size_t)u.pm * 2 + 0) * 2 + 1) * DFFC + c, acc[ai][1][0][n] * rs[ai][0]);
;                     st16_wt(PEND + (((size_t)u.pm * 2 + 1) * 2 + 0) * DFFC + c, a1); st16_wt(PEND + (((size_t)u.pm * 2 + 1) * 2 + 1) * DFFC + c, acc[ai][1][1][n] * rs[ai][1]); }
	v_pk_mul_f32 v[228:229], s[38:39], v[226:227] op_sel_hi:[0,1]
	v_exp_f32_e32 v226, v228
	v_exp_f32_e32 v227, v229
	s_nop 0
	v_pk_add_f32 v[228:229], s[36:37], v[226:227] op_sel_hi:[0,1]
	v_rcp_f32_e32 v226, v228
	v_rcp_f32_e32 v227, v229
	s_nop 0
	v_pk_mul_f32 v[228:229], v[220:221], v[226:227]
	v_pk_mul_f32 v[220:221], v[208:209], v[228:229]
	v_cvt_pk_bf16_f32 v217, v220, v221
	v_pk_mul_f32 v[208:209], v[78:79], v[216:217] op_sel_hi:[1,0]
	v_pk_mul_f32 v[166:167], v[126:127], v[224:225] op_sel_hi:[1,0]
	v_pk_fma_f32 v[220:221], v[166:167], v[150:151], v[138:139]
	v_pk_fma_f32 v[226:227], v[162:163], v[142:143], v[220:221]
	v_pk_fma_f32 v[220:221], v[158:159], v[146:147], v[226:227]
	v_pk_mul_f32 v[226:227], s[40:41], v[220:221] op_sel_hi:[0,1]
	v_pk_fma_f32 v[228:229], v[220:221], v[226:227], s[42:43] op_sel_hi:[1,1,0]
	v_pk_mul_f32 v[226:227], v[220:221], v[228:229]
	v_pk_mul_f32 v[228:229], s[38:39], v[226:227] op_sel_hi:[0,1]
	v_exp_f32_e32 v226, v228
	v_exp_f32_e32 v227, v229
	s_nop 0
	v_pk_add_f32 v[228:229], s[36:37], v[226:227] op_sel_hi:[0,1]
	v_rcp_f32_e32 v226, v228
	v_rcp_f32_e32 v227, v229
	s_nop 0
	v_pk_mul_f32 v[228:229], v[220:221], v[226:227]
	v_pk_mul_f32 v[220:221], v[208:209], v[228:229]
	v_cvt_pk_bf16_f32 v248, v220, v221
	v_pk_mul_f32 v[208:209], v[84:85], v[222:223] op_sel_hi:[1,0]
	v_mov_b32_e32 v220, v168
	v_mov_b32_e32 v221, v169
	s_nop 1
	v_mov_b32_dpp v220, v152 row_shr:1 row_mask:0xf bank_mask:0xf
	v_mov_b32_dpp v221, v153 row_shr:1 row_mask:0xf bank_mask:0xf
	v_pk_fma_f32 v[168:169], v[148:149], v[220:221], v[136:137]
	v_pk_fma_f32 v[148:149], v[164:165], v[140:141], v[168:169]
	v_pk_fma_f32 v[168:169], v[160:161], v[144:145], v[148:149]
	v_pk_mul_f32 v[144:145], s[40:41], v[168:169] op_sel_hi:[0,1]
	v_pk_fma_f32 v[148:149], v[168:169], v[144:145], s[42:43] op_sel_hi:[1,1,0]
	v_pk_mul_f32 v[144:145], v[168:169], v[148:149]
	v_pk_mul_f32 v[148:149], s[38:39], v[144:145] op_sel_hi:[0,1]
	v_exp_f32_e32 v144, v148
	v_exp_f32_e32 v145, v149
	s_nop 0
	v_pk_add_f32 v[148:149], s[36:37], v[144:145] op_sel_hi:[0,1]
	v_rcp_f32_e32 v144, v148
	v_rcp_f32_e32 v145, v149
	s_nop 0
	v_pk_mul_f32 v[148:149], v[168:169], v[144:145]
	v_pk_mul_f32 v[144:145], v[208:209], v[148:149]
	v_cvt_pk_bf16_f32 v251, v144, v145
	v_pk_mul_f32 v[144:145], v[86:87], v[222:223] op_sel_hi:[1,0]
	v_mov_b32_e32 v148, v170
	v_mov_b32_e32 v149, v171
	s_nop 1
	v_mov_b32_dpp v148, v154 row_shr:1 row_mask:0xf bank_mask:0xf
	v_mov_b32_dpp v149, v155 row_shr:1 row_mask:0xf bank_mask:0xf
	v_pk_fma_f32 v[168:169], v[150:151], v[148:149], v[138:139]
	v_pk_fma_f32 v[170:171], v[166:167], v[142:143], v[168:169]
	v_pk_fma_f32 v[168:169], v[162:163], v[146:147], v[170:171]
	v_pk_mul_f32 v[170:171], s[40:41], v[168:169] op_sel_hi:[0,1]
	v_pk_fma_f32 v[208:209], v[168:169], v[170:171], s[42:43] op_sel_hi:[1,1,0]
	v_pk_mul_f32 v[170:171], v[168:169], v[208:209]
	v_pk_mul_f32 v[208:209], s[38:39], v[170:171] op_sel_hi:[0,1]
	v_exp_f32_e32 v170, v208
	v_exp_f32_e32 v171, v209
	s_nop 0
	v_pk_add_f32 v[208:209], s[36:37], v[170:171] op_sel_hi:[0,1]
	v_rcp_f32_e32 v170, v208
	v_rcp_f32_e32 v171, v209
	s_nop 0
	v_pk_mul_f32 v[208:209], v[168:169], v[170:171]
	v_pk_mul_f32 v[168:169], v[144:145], v[208:209]
	v_cvt_pk_bf16_f32 v255, v168, v169
	v_cvt_pk_bf16_f32 v254, v132, v173
	v_pk_mul_f32 v[144:145], v[94:95], v[224:225] op_sel_hi:[1,0]
	v_mov_b32_e32 v168, v174
	v_mov_b32_e32 v169, v175
	s_nop 1
	v_mov_b32_dpp v168, v158 row_shr:1 row_mask:0xf bank_mask:0xf
	v_mov_b32_dpp v169, v159 row_shr:1 row_mask:0xf bank_mask:0xf
	v_pk_fma_f32 v[170:171], v[150:151], v[168:169], v[138:139]
	v_pk_fma_f32 v[168:169], v[142:143], v[148:149], v[170:171]
	v_pk_fma_f32 v[148:149], v[166:167], v[146:147], v[168:169]
	v_pk_mul_f32 v[168:169], s[40:41], v[148:149] op_sel_hi:[0,1]
	v_pk_fma_f32 v[170:171], v[148:149], v[168:169], s[42:43] op_sel_hi:[1,1,0]
	v_pk_mul_f32 v[168:169], v[148:149], v[170:171]
	v_pk_mul_f32 v[170:171], s[38:39], v[168:169] op_sel_hi:[0,1]
	v_exp_f32_e32 v168, v170
	v_exp_f32_e32 v169, v171
	s_nop 0
	v_pk_add_f32 v[170:171], s[36:37], v[168:169] op_sel_hi:[0,1]
	v_rcp_f32_e32 v168, v170
	v_rcp_f32_e32 v169, v171
	s_nop 0
	v_pk_mul_f32 v[170:171], v[148:149], v[168:169]
	v_pk_mul_f32 v[148:149], v[144:145], v[170:171]
	v_cvt_pk_bf16_f32 v151, v148, v149
	v_mov_b32_e32 v223, v222
	v_mov_b32_e32 v136, v218
	v_mov_b32_e32 v137, v219
	v_mov_b32_e32 v138, v172
	v_mov_b32_e32 v139, v215
	v_mov_b32_e32 v140, v173
	v_mov_b32_e32 v141, v245
	v_mov_b32_e32 v142, v217
	v_mov_b32_e32 v143, v248
	v_mov_b32_e32 v146, v251
	v_mov_b32_e32 v147, v255
	v_mov_b32_e32 v150, v254
	s_and_saveexec_b64 s[6:7], s[30:31]
	s_cbranch_execz .LBB0_409
	v_readlane_b32 s16, v249, 9
	s_add_u32 s16, s16, s68
	v_readlane_b32 s17, v249, 11
	s_addc_u32 s17, s17, s65
	v_mov_b32_e32 v140, v224
	v_lshl_add_u64 v[132:133], v[198:199], 2, s[16:17]
	s_mov_b64 s[16:17], 0x5800
	global_store_dwordx4 v[132:133], v[164:167], off sc1
	s_nop 1
	v_lshl_add_u64 v[136:137], v[132:133], 0, s[16:17]
	v_mov_b32_e32 v141, v224
	s_mov_b64 s[16:17], 0xb000
	v_pk_mul_f32 v[166:167], v[94:95], v[140:141]
	v_pk_mul_f32 v[164:165], v[92:93], v[224:225]
	s_nop 0
	global_store_dwordx4 v[136:137], v[164:167], off sc1
	s_nop 1
	v_lshl_add_u64 v[136:137], v[132:133], 0, s[16:17]
	global_store_dwordx4 v[136:137], v[160:163], off sc1
	s_nop 1
	s_mov_b64 s[16:17], 0x10800
	v_mov_b32_e32 v136, v222
	v_mov_b32_e32 v137, v222
	v_lshl_add_u64 v[132:133], v[132:133], 0, s[16:17]
	v_pk_mul_f32 v[162:163], v[86:87], v[136:137]
	v_pk_mul_f32 v[160:161], v[84:85], v[222:223]
	s_nop 0
	global_store_dwordx4 v[132:133], v[160:163], off sc1
	s_nop 1

;     __device__ __forceinline__ void operator()(const f32x4 (&acc)[2][2][4][2], const Unit& u, int wr, int wc, int fr, int fq) const {
;     ...
;         const bool prompt = u.pm < PROMPT_TILES;
; #pragma unroll
;         for (int ai = 0; ai < 2; ++ai) { const int blk = 2 * ai + wr; const bool pend = prompt && blk == 0 && (u.pm & 15) != 0;
;             const int sb = (u.pm - PROMPT_TILES) * 4 + blk;
;             u32x2 pk[4][2];
; #pragma unroll
;             for (int n = 0; n < 2; ++n) { const int c = col + 4 * n;
;                 const f32x4 w0 = *(const f32x4*)(cw + c), w1 = *(const f32x4*)(cw + DFFC + c), w2 = *(const f32x4*)(cw + 2 * DFFC + c), bb = *(const f32x4*)(cb + c);
;                 f32x4 h2, h3;
;                 if (!prompt) { h2 = *(const f32x4*)(state + ((size_t)sb * 2 + 0) * DFFC + c); h3 = *(const f32x4*)(state + ((size_t)sb * 2 + 1) * DFFC + c); }
;                 else if (blk > 0) { h2 = *(const PG8_LAS f32x4*)(xch + (((blk - 1) * 2 + 0) * 4 + wc) * 32 + 8 * fq + 4 * n); h3 = *(const PG8_LAS f32x4*)(xch + (((blk - 1) * 2 + 1) * 4 + wc) * 32 + 8 * fq + 4 * n); }
;                 else { h2 = (f32x4){0.f, 0.f, 0.f, 0.f}; h3 = h2; }
;                 const f32x4 a0 = acc[ai][0][0][n] * rs[ai][0], a1 = acc[ai][0][1][n] * rs[ai][1], a2 = acc[ai][0][2][n] * rs[ai][2], a3 = acc[ai][0][3][n] * rs[ai][3];
;                 f32x4 o0, o1, o2, o3;
; #pragma unroll
;                 for (int j = 0; j < 4; ++j) { const float p3 = dpp_up(h3[j], a3[j]), p2 = dpp_up(h2[j], a2[j]);
;                     o0[j] = gelu_tanh(bb[j] + w0[j] * p2 + w1[j] * p3 + w2[j] * a0[j]) * (acc[ai][1][0][n][j] * rs[ai][0]);
;                     o1[j] = gelu_tanh(bb[j] + w0[j] * p3 + w1[j] * a0[j] + w2[j] * a1[j]) * (acc[ai][1][1][n][j] * rs[ai][1]);
;                     o2[j] = gelu_tanh(bb[j] + w0[j] * a0[j] + w1[j] * a1[j] + w2[j] * a2[j]) * (acc[ai][1][2][n][j] * rs[ai][2]);
;                     o3[j] = gelu_tanh(bb[j] + w0[j] * a1[j] + w1[j] * a2[j] + w2[j] * a3[j]) * (acc[ai][1][3][n][j] * rs[ai][3]); }
;                 pk[0][n].x = cvt_pk_bf16(o0[0], o0[1]); pk[0][n].y = cvt_pk_bf16(o0[2], o0[3]); pk[1][n].x = cvt_pk_bf16(o1[0], o1[1]); pk[1][n].y = cvt_pk_bf16(o1[2], o1[3]);
;                 pk[2][n].x = cvt_pk_bf16(o2[0], o2[1]); pk[2][n].y = cvt_pk_bf16(o2[2], o2[3]); pk[3][n].x = cvt_pk_bf16(o3[0], o3[1]); pk[3][n].y = cvt_pk_bf16(o3[2], o3[3]);
.LBB0_440:
	v_fmamk_f32 v128, v128, 0x3a000000, v244
	v_rsq_f32_e32 v180, v128
	v_fmamk_f32 v128, v129, 0x3a000000, v244
	v_rsq_f32_e32 v178, v128
	v_pk_mul_f32 v[146:147], v[44:45], v[202:203] op_sel_hi:[1,0]
	v_pk_mul_f32 v[142:143], v[36:37], v[200:201] op_sel_hi:[1,0]
	v_pk_mul_f32 v[166:167], v[60:61], v[180:181] op_sel_hi:[1,0]
	s_waitcnt vmcnt(1) lgkmcnt(1)
	v_mov_b32_dpp v158, v146 row_shr:1 row_mask:0xf bank_mask:0xf
	s_waitcnt vmcnt(0) lgkmcnt(0)
	v_readlane_b32 s0, v249, 35
	s_nop 1
	v_readlane_b32 s1, v249, 36
	s_nop 1
	s_and_b64 s[0:1], s[0:1], s[16:17]
	s_mov_b32 s6, 1.0
	s_mov_b32 s30, 0xbfb8aa3b
	s_mov_b32 s36, 0x3d922279
	s_mov_b32 s38, 0x3fcc422a
	v_pk_mul_f32 v[162:163], v[4:5], v[200:201] op_sel_hi:[1,0]
	v_pk_mul_f32 v[164:165], v[52:53], v[178:179] op_sel_hi:[1,0]
	v_pk_fma_f32 v[182:183], v[164:165], v[150:151], v[130:131]
	v_pk_fma_f32 v[210:211], v[146:147], v[138:139], v[182:183]
	v_pk_fma_f32 v[182:183], v[142:143], v[134:135], v[210:211]
	v_pk_mul_f32 v[210:211], s[36:37], v[182:183] op_sel_hi:[0,1]
	v_pk_fma_f32 v[212:213], v[182:183], v[210:211], s[38:39] op_sel_hi:[1,1,0]
	v_pk_mul_f32 v[210:211], v[182:183], v[212:213]
	v_pk_mul_f32 v[212:213], s[30:31], v[210:211] op_sel_hi:[0,1]
	v_exp_f32_e32 v210, v212
	v_exp_f32_e32 v211, v213
	s_nop 0
	v_pk_add_f32 v[212:213], s[6:7], v[210:211] op_sel_hi:[0,1]
	v_rcp_f32_e32 v210, v212
	v_rcp_f32_e32 v211, v213
	s_nop 0
	v_pk_mul_f32 v[212:213], v[182:183], v[210:211]
	v_pk_mul_f32 v[182:183], v[162:163], v[212:213]
	v_cvt_pk_bf16_f32 v128, v182, v183
	v_pk_mul_f32 v[162:163], v[6:7], v[200:201] op_sel_hi:[1,0]
	v_pk_mul_f32 v[144:145], v[38:39], v[200:201] op_sel_hi:[1,0]
	v_pk_mul_f32 v[148:149], v[46:47], v[202:203] op_sel_hi:[1,0]
	v_pk_mul_f32 v[210:211], v[54:55], v[178:179] op_sel_hi:[1,0]
	v_pk_fma_f32 v[212:213], v[210:211], v[152:153], v[132:133]
	v_pk_fma_f32 v[214:215], v[148:149], v[140:141], v[212:213]
	v_pk_fma_f32 v[212:213], v[144:145], v[136:137], v[214:215]
	v_pk_mul_f32 v[214:215], s[36:37], v[212:213] op_sel_hi:[0,1]
	v_pk_fma_f32 v[216:217], v[212:213], v[214:215], s[38:39] op_sel_hi:[1,1,0]
	v_pk_mul_f32 v[214:215], v[212:213], v[216:217]
	v_pk_mul_f32 v[216:217], s[30:31], v[214:215] op_sel_hi:[0,1]
	v_exp_f32_e32 v214, v216
	v_exp_f32_e32 v215, v217
	s_nop 0
	v_pk_add_f32 v[216:217], s[6:7], v[214:215] op_sel_hi:[0,1]
	v_rcp_f32_e32 v214, v216
	v_rcp_f32_e32 v215, v217
	s_nop 0
	v_pk_mul_f32 v[216:217], v[212:213], v[214:215]
	v_pk_mul_f32 v[212:213], v[162:163], v[216:217]
	v_cvt_pk_bf16_f32 v129, v212, v213
	v_pk_mul_f32 v[162:163], v[12:13], v[202:203] op_sel_hi:[1,0]
	v_pk_fma_f32 v[212:213], v[166:167], v[150:151], v[130:131]
	v_pk_fma_f32 v[214:215], v[164:165], v[138:139], v[212:213]
	v_pk_fma_f32 v[212:213], v[146:147], v[134:135], v[214:215]
	v_pk_mul_f32 v[214:215], s[36:37], v[212:213] op_sel_hi:[0,1]
	v_pk_fma_f32 v[216:217], v[212:213], v[214:215], s[38:39] op_sel_hi:[1,1,0]
	v_pk_mul_f32 v[214:215], v[212:213], v[216:217]
	v_pk_mul_f32 v[216:217], s[30:31], v[214:215] op_sel_hi:[0,1]
	v_exp_f32_e32 v214, v216
	v_exp_f32_e32 v215, v217
	s_nop 0
	v_pk_add_f32 v[216:217], s[6:7], v[214:215] op_sel_hi:[0,1]
	v_rcp_f32_e32 v214, v216
	v_rcp_f32_e32 v215, v217
	s_nop 0
	v_pk_mul_f32 v[216:217], v[212:213], v[214:215]
	v_pk_mul_f32 v[212:213], v[162:163], v[216:217]
	v_cvt_pk_bf16_f32 v245, v212, v213
	v_pk_mul_f32 v[162:163], v[14:15], v[202:203] op_sel_hi:[1,0]
	v_pk_mul_f32 v[212:213], v[62:63], v[180:181] op_sel_hi:[1,0]
	v_pk_fma_f32 v[214:215], v[212:213], v[152:153], v[132:133]
	v_pk_fma_f32 v[216:217], v[210:211], v[140:141], v[214:215]
	v_pk_fma_f32 v[214:215], v[148:149], v[136:137], v[216:217]
	v_pk_mul_f32 v[216:217], s[36:37], v[214:215] op_sel_hi:[0,1]
	v_pk_fma_f32 v[222:223], v[214:215], v[216:217], s[38:39] op_sel_hi:[1,1,0]
	v_pk_mul_f32 v[216:217], v[214:215], v[222:223]
	v_pk_mul_f32 v[222:223], s[30:31], v[216:217] op_sel_hi:[0,1]
	v_exp_f32_e32 v216, v222
	v_exp_f32_e32 v217, v223
	s_nop 0
	v_pk_add_f32 v[222:223], s[6:7], v[216:217] op_sel_hi:[0,1]
	v_rcp_f32_e32 v216, v222
	v_rcp_f32_e32 v217, v223
	s_nop 0
	v_pk_mul_f32 v[222:223], v[214:215], v[216:217]
	v_pk_mul_f32 v[214:215], v[162:163], v[222:223]
	v_cvt_pk_bf16_f32 v248, v214, v215
	v_pk_mul_f32 v[162:163], v[20:21], v[178:179] op_sel_hi:[1,0]
	v_mov_b32_e32 v214, v154
	v_mov_b32_e32 v215, v155
	s_nop 1
	v_mov_b32_dpp v214, v142 row_shr:1 row_mask:0xf bank_mask:0xf
	v_mov_b32_dpp v215, v143 row_shr:1 row_mask:0xf bank_mask:0xf
; __device__ __forceinline__ unsigned cvt_pk_bf16(float lo, float hi) { unsigned r; asm volatile("v_cvt_pk_bf16_f32 %0, %1, %2" : "=v"(r) : "v"(lo), "v"(hi)); return r; }
; __device__ __forceinline__ void st16_wt(void* p, f32x4 v) { asm volatile("global_store_dwordx4 %0, %1, off sc1\n\ts_nop 1" :: "v"(p), "v"(v) : "memory"); }
; __device__ __forceinline__ float gelu_tanh(float x) { const float u = x * (1.5957691216057308f + 0.0713548162726009f * x * x); return x * sigmoid_f(u); }
;     __device__ __forceinline__ static float dpp_up(float old, float src) { return __builtin_bit_cast(float, __builtin_amdgcn_update_dpp(__builtin_bit_cast(int, old), __builtin_bit_cast(int, src), 0x111, 0xf, 0xf, false)); }
;     __device__ __forceinline__ void operator()(const f32x4 (&acc)[2][2][4][2], const Unit& u, int wr, int wc, int fr, int fq) const {
;     ...
;                 const f32x4 a0 = acc[ai][0][0][n] * rs[ai][0], a1 = acc[ai][0][1][n] * rs[ai][1], a2 = acc[ai][0][2][n] * rs[ai][2], a3 = acc[ai][0][3][n] * rs[ai][3];
;                 f32x4 o0, o1, o2, o3;
; #pragma unroll
;                 for (int j = 0; j < 4; ++j) { const float p3 = dpp_up(h3[j], a3[j]), p2 = dpp_up(h2[j], a2[j]);
;                     o0[j] = gelu_tanh(bb[j] + w0[j] * p2 + w1[j] * p3 + w2[j] * a0[j]) * (acc[ai][1][0][n][j] * rs[ai][0]);
;                     o1[j] = gelu_tanh(bb[j] + w0[j] * p3 + w1[j] * a0[j] + w2[j] * a1[j]) * (acc[ai][1][1][n][j] * rs[ai][1]);
;                     o2[j] = gelu_tanh(bb[j] + w0[j] * a0[j] + w1[j] * a1[j] + w2[j] * a2[j]) * (acc[ai][1][2][n][j] * rs[ai][2]);
;                     o3[j] = gelu_tanh(bb[j] + w0[j] * a1[j] + w1[j] * a2[j] + w2[j] * a3[j]) * (acc[ai][1][3][n][j] * rs[ai][3]); }
;                 pk[0][n].x = cvt_pk_bf16(o0[0], o0[1]); pk[0][n].y = cvt_pk_bf16(o0[2], o0[3]); pk[1][n].x = cvt_pk_bf16(o1[0], o1[1]); pk[1][n].y = cvt_pk_bf16(o1[2], o1[3]);
;                 pk[2][n].x = cvt_pk_bf16(o2[0], o2[1]); pk[2][n].y = cvt_pk_bf16(o2[2], o2[3]); pk[3][n].x = cvt_pk_bf16(o3[0], o3[1]); pk[3][n].y = cvt_pk_bf16(o3[2], o3[3]);
;                 if (pend && fr == 0) {
;                     st16_wt(PEND + (((size_t)u.pm * 2 + 0) * 2 + 0) * DFFC + c, a0); st16_wt(PEND + (((size_t)u.pm * 2 + 0) * 2 + 1) * DFFC + c, acc[ai][1][0][n] * rs[ai][0]);
	v_pk_fma_f32 v[216:217], v[150:151], v[214:215], v[130:131]
	v_pk_fma_f32 v[214:215], v[166:167], v[138:139], v[216:217]
	v_pk_fma_f32 v[216:217], v[164:165], v[134:135], v[214:215]
	v_pk_mul_f32 v[164:165], s[36:37], v[216:217] op_sel_hi:[0,1]
	v_pk_fma_f32 v[214:215], v[216:217], v[164:165], s[38:39] op_sel_hi:[1,1,0]
	v_pk_mul_f32 v[164:165], v[216:217], v[214:215]
	v_pk_mul_f32 v[214:215], s[30:31], v[164:165] op_sel_hi:[0,1]
	v_exp_f32_e32 v164, v214
	v_exp_f32_e32 v165, v215
	s_nop 0
	v_pk_add_f32 v[214:215], s[6:7], v[164:165] op_sel_hi:[0,1]
	v_rcp_f32_e32 v164, v214
	v_rcp_f32_e32 v165, v215
	s_nop 0
	v_pk_mul_f32 v[214:215], v[216:217], v[164:165]
	v_pk_mul_f32 v[164:165], v[162:163], v[214:215]
	v_cvt_pk_bf16_f32 v251, v164, v165
	v_pk_mul_f32 v[162:163], v[22:23], v[178:179] op_sel_hi:[1,0]
	v_mov_b32_e32 v164, v156
	v_mov_b32_e32 v165, v157
	s_nop 1
	v_mov_b32_dpp v164, v144 row_shr:1 row_mask:0xf bank_mask:0xf
	v_mov_b32_dpp v165, v145 row_shr:1 row_mask:0xf bank_mask:0xf
	v_pk_fma_f32 v[156:157], v[152:153], v[164:165], v[132:133]
	v_pk_fma_f32 v[214:215], v[212:213], v[140:141], v[156:157]
	v_pk_fma_f32 v[156:157], v[210:211], v[136:137], v[214:215]
	v_pk_mul_f32 v[210:211], s[36:37], v[156:157] op_sel_hi:[0,1]
	v_pk_fma_f32 v[214:215], v[156:157], v[210:211], s[38:39] op_sel_hi:[1,1,0]
	v_pk_mul_f32 v[210:211], v[156:157], v[214:215]
	v_pk_mul_f32 v[214:215], s[30:31], v[210:211] op_sel_hi:[0,1]
	v_exp_f32_e32 v210, v214
	v_exp_f32_e32 v211, v215
	s_nop 0
	v_pk_add_f32 v[214:215], s[6:7], v[210:211] op_sel_hi:[0,1]
	v_rcp_f32_e32 v210, v214
	v_rcp_f32_e32 v211, v215
	s_nop 0
	v_pk_mul_f32 v[214:215], v[156:157], v[210:211]
	v_pk_mul_f32 v[156:157], v[162:163], v[214:215]
	v_cvt_pk_bf16_f32 v255, v156, v157
	v_mul_f32_e32 v254, v28, v180
	v_mov_b32_e32 v253, v154
	s_nop 1
	v_mov_b32_dpp v253, v142 row_shr:1 row_mask:0xf bank_mask:0xf
	v_fma_f32 v154, v150, v158, v130
	v_fma_f32 v150, v138, v253, v154
	v_fma_f32 v138, v166, v134, v150
	v_mul_f32_e32 v134, 0x3d922279, v138
	v_fmaak_f32 v150, v138, v134, 0x3fcc422a
	v_mul_f32_e32 v134, v138, v150
	v_mul_f32_e32 v150, 0xbfb8aa3b, v134
	v_exp_f32_e32 v134, v150
	s_nop 0
	v_add_f32_e32 v150, 1.0, v134
	v_rcp_f32_e32 v134, v150
	s_nop 0
	v_mul_f32_e32 v150, v138, v134
	v_mul_f32_e32 v134, v254, v150
	v_mul_f32_e32 v138, v29, v180
	v_mov_b32_e32 v150, v155
	s_nop 1
	v_mov_b32_dpp v150, v143 row_shr:1 row_mask:0xf bank_mask:0xf
	v_mov_b32_e32 v158, v159
	s_nop 1
	v_mov_b32_dpp v158, v147 row_shr:1 row_mask:0xf bank_mask:0xf
	v_fma_f32 v159, v151, v158, v131
	v_fma_f32 v151, v139, v150, v159
	v_fma_f32 v139, v167, v135, v151
	v_mul_f32_e32 v135, 0x3d922279, v139
	v_fmaak_f32 v254, v139, v135, 0x3fcc422a
	v_mul_f32_e32 v135, v139, v254
	v_mul_f32_e32 v254, 0xbfb8aa3b, v135
	v_exp_f32_e32 v135, v254
	s_nop 0
	v_add_f32_e32 v254, 1.0, v135
	v_rcp_f32_e32 v135, v254
	s_nop 0
	v_mul_f32_e32 v254, v139, v135
	v_mul_f32_e32 v135, v138, v254
	v_cvt_pk_bf16_f32 v254, v134, v135
	v_pk_mul_f32 v[134:135], v[30:31], v[180:181] op_sel_hi:[1,0]
	v_mov_b32_e32 v138, v160
	v_mov_b32_e32 v139, v161
	s_nop 1
	v_mov_b32_dpp v138, v148 row_shr:1 row_mask:0xf bank_mask:0xf
	v_mov_b32_dpp v139, v149 row_shr:1 row_mask:0xf bank_mask:0xf
	v_pk_fma_f32 v[150:151], v[152:153], v[138:139], v[132:133]
	v_pk_fma_f32 v[138:139], v[140:141], v[164:165], v[150:151]
	v_pk_fma_f32 v[150:151], v[212:213], v[136:137], v[138:139]
	v_pk_mul_f32 v[138:139], s[36:37], v[150:151] op_sel_hi:[0,1]
	v_pk_fma_f32 v[152:153], v[150:151], v[138:139], s[38:39] op_sel_hi:[1,1,0]
	v_pk_mul_f32 v[138:139], v[150:151], v[152:153]
	v_pk_mul_f32 v[152:153], s[30:31], v[138:139] op_sel_hi:[0,1]
	v_exp_f32_e32 v138, v152
	v_exp_f32_e32 v139, v153
	s_nop 0
	v_pk_add_f32 v[152:153], s[6:7], v[138:139] op_sel_hi:[0,1]
	v_rcp_f32_e32 v138, v152
	v_rcp_f32_e32 v139, v153
	s_nop 0
	v_pk_mul_f32 v[152:153], v[150:151], v[138:139]
	v_pk_mul_f32 v[138:139], v[134:135], v[152:153]
	v_cvt_pk_bf16_f32 v141, v138, v139
	v_mul_f32_e32 v168, v12, v202
	v_mov_b32_e32 v130, v182
	v_mov_b32_e32 v131, v183
	v_mov_b32_e32 v132, v245
	v_mov_b32_e32 v133, v248
	v_mov_b32_e32 v136, v251
	v_mov_b32_e32 v137, v255
	v_mov_b32_e32 v140, v254
	s_and_saveexec_b64 s[6:7], s[8:9]
	s_cbranch_execz .LBB0_448
	s_and_b64 vcc, exec, s[14:15]
	s_cbranch_vccnz .LBB0_443
	v_readlane_b32 s16, v249, 19
	s_add_u32 s16, s16, s55
	v_readlane_b32 s17, v249, 21
	s_addc_u32 s17, s17, s53
	s_mov_b64 s[30:31], -1
	s_cbranch_execz .LBB0_444
	s_branch .LBB0_446

; __device__ __forceinline__ unsigned cvt_pk_bf16(float lo, float hi) { unsigned r; asm volatile("v_cvt_pk_bf16_f32 %0, %1, %2" : "=v"(r) : "v"(lo), "v"(hi)); return r; }
; __device__ __forceinline__ float gelu_tanh(float x) { const float u = x * (1.5957691216057308f + 0.0713548162726009f * x * x); return x * sigmoid_f(u); }
;     __device__ __forceinline__ static float dpp_up(float old, float src) { return __builtin_bit_cast(float, __builtin_amdgcn_update_dpp(__builtin_bit_cast(int, old), __builtin_bit_cast(int, src), 0x111, 0xf, 0xf, false)); }
;     __device__ __forceinline__ void operator()(const f32x4 (&acc)[2][2][4][2], const Unit& u, int wr, int wc, int fr, int fq) const {
;     ...
;                 const f32x4 a0 = acc[ai][0][0][n] * rs[ai][0], a1 = acc[ai][0][1][n] * rs[ai][1], a2 = acc[ai][0][2][n] * rs[ai][2], a3 = acc[ai][0][3][n] * rs[ai][3];
;                 f32x4 o0, o1, o2, o3;
; #pragma unroll
;                 for (int j = 0; j < 4; ++j) { const float p3 = dpp_up(h3[j], a3[j]), p2 = dpp_up(h2[j], a2[j]);
;                     o0[j] = gelu_tanh(bb[j] + w0[j] * p2 + w1[j] * p3 + w2[j] * a0[j]) * (acc[ai][1][0][n][j] * rs[ai][0]);
;                     o1[j] = gelu_tanh(bb[j] + w0[j] * p3 + w1[j] * a0[j] + w2[j] * a1[j]) * (acc[ai][1][1][n][j] * rs[ai][1]);
;                     o2[j] = gelu_tanh(bb[j] + w0[j] * a0[j] + w1[j] * a1[j] + w2[j] * a2[j]) * (acc[ai][1][2][n][j] * rs[ai][2]);
;                     o3[j] = gelu_tanh(bb[j] + w0[j] * a1[j] + w1[j] * a2[j] + w2[j] * a3[j]) * (acc[ai][1][3][n][j] * rs[ai][3]); }
;                 pk[0][n].x = cvt_pk_bf16(o0[0], o0[1]); pk[0][n].y = cvt_pk_bf16(o0[2], o0[3]); pk[1][n].x = cvt_pk_bf16(o1[0], o1[1]); pk[1][n].y = cvt_pk_bf16(o1[2], o1[3]);
;                 pk[2][n].x = cvt_pk_bf16(o2[0], o2[1]); pk[2][n].y = cvt_pk_bf16(o2[2], o2[3]); pk[3][n].x = cvt_pk_bf16(o3[0], o3[1]); pk[3][n].y = cvt_pk_bf16(o3[2], o3[3]);
.LBB0_452:
	v_mov_b32_e32 v203, v202
	v_mov_b32_e32 v144, v202
	v_mov_b32_e32 v145, v202
	v_mov_b32_e32 v201, v200
	v_pk_mul_f32 v[150:151], v[42:43], v[144:145]
	v_pk_mul_f32 v[148:149], v[40:41], v[202:203]
	v_mov_b32_e32 v144, v200
	v_mov_b32_e32 v145, v200
	v_pk_mul_f32 v[146:147], v[34:35], v[144:145]
	v_pk_mul_f32 v[144:145], v[32:33], v[200:201]
	s_waitcnt vmcnt(1) lgkmcnt(1)
	v_mov_b32_dpp v172, v148 row_shr:1 row_mask:0xf bank_mask:0xf
	v_mov_b32_e32 v181, v180
	s_waitcnt vmcnt(0) lgkmcnt(0)
	s_mov_b32 s6, 1.0
	s_mov_b32 s30, 0xbfb8aa3b
	s_mov_b32 s36, 0x3d922279
	s_mov_b32 s38, 0x3fcc422a
	v_pk_mul_f32 v[182:183], v[0:1], v[200:201] op_sel_hi:[1,0]
	v_pk_mul_f32 v[204:205], v[48:49], v[178:179] op_sel_hi:[1,0]
	v_pk_fma_f32 v[206:207], v[204:205], v[164:165], v[152:153]
	v_pk_fma_f32 v[210:211], v[148:149], v[160:161], v[206:207]
	v_pk_fma_f32 v[206:207], v[144:145], v[156:157], v[210:211]
	v_pk_mul_f32 v[210:211], s[36:37], v[206:207] op_sel_hi:[0,1]
	v_pk_fma_f32 v[212:213], v[206:207], v[210:211], s[38:39] op_sel_hi:[1,1,0]
	v_pk_mul_f32 v[210:211], v[206:207], v[212:213]
	v_pk_mul_f32 v[212:213], s[30:31], v[210:211] op_sel_hi:[0,1]
	v_exp_f32_e32 v210, v212
	v_exp_f32_e32 v211, v213
	s_nop 0
	v_pk_add_f32 v[212:213], s[6:7], v[210:211] op_sel_hi:[0,1]
	v_rcp_f32_e32 v210, v212
	v_rcp_f32_e32 v211, v213
	s_nop 0
	v_pk_mul_f32 v[212:213], v[206:207], v[210:211]
	v_pk_mul_f32 v[206:207], v[182:183], v[212:213]
	v_cvt_pk_bf16_f32 v130, v206, v207
	v_pk_mul_f32 v[182:183], v[2:3], v[200:201] op_sel_hi:[1,0]
	v_pk_mul_f32 v[200:201], v[50:51], v[178:179] op_sel_hi:[1,0]
	v_pk_fma_f32 v[210:211], v[200:201], v[166:167], v[154:155]
	v_pk_fma_f32 v[212:213], v[150:151], v[162:163], v[210:211]
	v_pk_fma_f32 v[210:211], v[146:147], v[158:159], v[212:213]
	v_pk_mul_f32 v[212:213], s[36:37], v[210:211] op_sel_hi:[0,1]
	v_pk_fma_f32 v[214:215], v[210:211], v[212:213], s[38:39] op_sel_hi:[1,1,0]
	v_pk_mul_f32 v[212:213], v[210:211], v[214:215]
	v_pk_mul_f32 v[214:215], s[30:31], v[212:213] op_sel_hi:[0,1]
	v_exp_f32_e32 v212, v214
	v_exp_f32_e32 v213, v215
	s_nop 0
	v_pk_add_f32 v[214:215], s[6:7], v[212:213] op_sel_hi:[0,1]
	v_rcp_f32_e32 v212, v214
	v_rcp_f32_e32 v213, v215
	s_nop 0
	v_pk_mul_f32 v[214:215], v[210:211], v[212:213]
	v_pk_mul_f32 v[210:211], v[182:183], v[214:215]
	v_cvt_pk_bf16_f32 v131, v210, v211
	v_pk_mul_f32 v[182:183], v[8:9], v[202:203] op_sel_hi:[1,0]
	v_pk_mul_f32 v[210:211], v[56:57], v[180:181]
	v_pk_fma_f32 v[212:213], v[210:211], v[164:165], v[152:153]
	v_pk_fma_f32 v[214:215], v[204:205], v[160:161], v[212:213]
	v_pk_fma_f32 v[212:213], v[148:149], v[156:157], v[214:215]
	v_pk_mul_f32 v[214:215], s[36:37], v[212:213] op_sel_hi:[0,1]
	v_pk_fma_f32 v[216:217], v[212:213], v[214:215], s[38:39] op_sel_hi:[1,1,0]
	v_pk_mul_f32 v[214:215], v[212:213], v[216:217]
	v_pk_mul_f32 v[216:217], s[30:31], v[214:215] op_sel_hi:[0,1]
	v_exp_f32_e32 v214, v216
	v_exp_f32_e32 v215, v217
	s_nop 0
	v_pk_add_f32 v[216:217], s[6:7], v[214:215] op_sel_hi:[0,1]
	v_rcp_f32_e32 v214, v216
	v_rcp_f32_e32 v215, v217
	s_nop 0
	v_pk_mul_f32 v[216:217], v[212:213], v[214:215]
	v_pk_mul_f32 v[212:213], v[182:183], v[216:217]
	v_cvt_pk_bf16_f32 v134, v212, v213
	v_pk_mul_f32 v[182:183], v[10:11], v[202:203] op_sel_hi:[1,0]
	v_pk_mul_f32 v[202:203], v[58:59], v[180:181] op_sel_hi:[1,0]
	v_pk_fma_f32 v[212:213], v[202:203], v[166:167], v[154:155]
	v_pk_fma_f32 v[214:215], v[200:201], v[162:163], v[212:213]
	v_pk_fma_f32 v[212:213], v[150:151], v[158:159], v[214:215]
	v_pk_mul_f32 v[214:215], s[36:37], v[212:213] op_sel_hi:[0,1]
	v_pk_fma_f32 v[216:217], v[212:213], v[214:215], s[38:39] op_sel_hi:[1,1,0]
	v_pk_mul_f32 v[214:215], v[212:213], v[216:217]
	v_pk_mul_f32 v[216:217], s[30:31], v[214:215] op_sel_hi:[0,1]
	v_exp_f32_e32 v214, v216
	v_exp_f32_e32 v215, v217
	s_nop 0
	v_pk_add_f32 v[216:217], s[6:7], v[214:215] op_sel_hi:[0,1]
	v_rcp_f32_e32 v214, v216
	v_rcp_f32_e32 v215, v217
	s_nop 0
	v_pk_mul_f32 v[216:217], v[212:213], v[214:215]
	v_pk_mul_f32 v[212:213], v[182:183], v[216:217]
	v_cvt_pk_bf16_f32 v135, v212, v213
	v_pk_mul_f32 v[182:183], v[16:17], v[178:179] op_sel_hi:[1,0]
	v_mov_b32_e32 v212, v168
	v_mov_b32_e32 v213, v169
	s_nop 1
	v_mov_b32_dpp v212, v144 row_shr:1 row_mask:0xf bank_mask:0xf
	v_mov_b32_dpp v213, v145 row_shr:1 row_mask:0xf bank_mask:0xf
; __device__ __forceinline__ unsigned cvt_pk_bf16(float lo, float hi) { unsigned r; asm volatile("v_cvt_pk_bf16_f32 %0, %1, %2" : "=v"(r) : "v"(lo), "v"(hi)); return r; }
; __device__ __forceinline__ void st16_wt(void* p, f32x4 v) { asm volatile("global_store_dwordx4 %0, %1, off sc1\n\ts_nop 1" :: "v"(p), "v"(v) : "memory"); }
; __device__ __forceinline__ float gelu_tanh(float x) { const float u = x * (1.5957691216057308f + 0.0713548162726009f * x * x); return x * sigmoid_f(u); }
;     __device__ __forceinline__ static float dpp_up(float old, float src) { return __builtin_bit_cast(float, __builtin_amdgcn_update_dpp(__builtin_bit_cast(int, old), __builtin_bit_cast(int, src), 0x111, 0xf, 0xf, false)); }
;     __device__ __forceinline__ void operator()(const f32x4 (&acc)[2][2][4][2], const Unit& u, int wr, int wc, int fr, int fq) const {
;     ...
;                 const f32x4 a0 = acc[ai][0][0][n] * rs[ai][0], a1 = acc[ai][0][1][n] * rs[ai][1], a2 = acc[ai][0][2][n] * rs[ai][2], a3 = acc[ai][0][3][n] * rs[ai][3];
;                 f32x4 o0, o1, o2, o3;
; #pragma unroll
;                 for (int j = 0; j < 4; ++j) { const float p3 = dpp_up(h3[j], a3[j]), p2 = dpp_up(h2[j], a2[j]);
;                     o0[j] = gelu_tanh(bb[j] + w0[j] * p2 + w1[j] * p3 + w2[j] * a0[j]) * (acc[ai][1][0][n][j] * rs[ai][0]);
;                     o1[j] = gelu_tanh(bb[j] + w0[j] * p3 + w1[j] * a0[j] + w2[j] * a1[j]) * (acc[ai][1][1][n][j] * rs[ai][1]);
;                     o2[j] = gelu_tanh(bb[j] + w0[j] * a0[j] + w1[j] * a1[j] + w2[j] * a2[j]) * (acc[ai][1][2][n][j] * rs[ai][2]);
;                     o3[j] = gelu_tanh(bb[j] + w0[j] * a1[j] + w1[j] * a2[j] + w2[j] * a3[j]) * (acc[ai][1][3][n][j] * rs[ai][3]); }
;                 pk[0][n].x = cvt_pk_bf16(o0[0], o0[1]); pk[0][n].y = cvt_pk_bf16(o0[2], o0[3]); pk[1][n].x = cvt_pk_bf16(o1[0], o1[1]); pk[1][n].y = cvt_pk_bf16(o1[2], o1[3]);
;                 pk[2][n].x = cvt_pk_bf16(o2[0], o2[1]); pk[2][n].y = cvt_pk_bf16(o2[2], o2[3]); pk[3][n].x = cvt_pk_bf16(o3[0], o3[1]); pk[3][n].y = cvt_pk_bf16(o3[2], o3[3]);
;                 if (pend && fr == 0) {
;                     st16_wt(PEND + (((size_t)u.pm * 2 + 0) * 2 + 0) * DFFC + c, a0); st16_wt(PEND + (((size_t)u.pm * 2 + 0) * 2 + 1) * DFFC + c, acc[ai][1][0][n] * rs[ai][0]);
	v_pk_fma_f32 v[214:215], v[164:165], v[212:213], v[152:153]
	v_pk_fma_f32 v[212:213], v[210:211], v[160:161], v[214:215]
	v_pk_fma_f32 v[210:211], v[204:205], v[156:157], v[212:213]
	v_pk_mul_f32 v[204:205], s[36:37], v[210:211] op_sel_hi:[0,1]
	v_pk_fma_f32 v[212:213], v[210:211], v[204:205], s[38:39] op_sel_hi:[1,1,0]
	v_pk_mul_f32 v[204:205], v[210:211], v[212:213]
	v_pk_mul_f32 v[212:213], s[30:31], v[204:205] op_sel_hi:[0,1]
	v_exp_f32_e32 v204, v212
	v_exp_f32_e32 v205, v213
	s_nop 0
	v_pk_add_f32 v[212:213], s[6:7], v[204:205] op_sel_hi:[0,1]
	v_rcp_f32_e32 v204, v212
	v_rcp_f32_e32 v205, v213
	s_nop 0
	v_pk_mul_f32 v[212:213], v[210:211], v[204:205]
	v_pk_mul_f32 v[204:205], v[182:183], v[212:213]
	v_cvt_pk_bf16_f32 v138, v204, v205
	v_pk_mul_f32 v[182:183], v[18:19], v[178:179] op_sel_hi:[1,0]
	v_mov_b32_e32 v178, v170
	v_mov_b32_e32 v179, v171
	s_nop 1
	v_mov_b32_dpp v178, v146 row_shr:1 row_mask:0xf bank_mask:0xf
	v_mov_b32_dpp v179, v147 row_shr:1 row_mask:0xf bank_mask:0xf
	v_pk_fma_f32 v[170:171], v[166:167], v[178:179], v[154:155]
	v_pk_fma_f32 v[204:205], v[202:203], v[162:163], v[170:171]
	v_pk_fma_f32 v[170:171], v[200:201], v[158:159], v[204:205]
	v_pk_mul_f32 v[200:201], s[36:37], v[170:171] op_sel_hi:[0,1]
	v_pk_fma_f32 v[204:205], v[170:171], v[200:201], s[38:39] op_sel_hi:[1,1,0]
	v_pk_mul_f32 v[200:201], v[170:171], v[204:205]
	v_pk_mul_f32 v[204:205], s[30:31], v[200:201] op_sel_hi:[0,1]
	v_exp_f32_e32 v200, v204
	v_exp_f32_e32 v201, v205
	s_nop 0
	v_pk_add_f32 v[204:205], s[6:7], v[200:201] op_sel_hi:[0,1]
	v_rcp_f32_e32 v200, v204
	v_rcp_f32_e32 v201, v205
	s_nop 0
	v_pk_mul_f32 v[204:205], v[170:171], v[200:201]
	v_pk_mul_f32 v[170:171], v[182:183], v[204:205]
	v_cvt_pk_bf16_f32 v139, v170, v171
	v_mul_f32_e32 v245, v24, v180
	v_mul_f32_e32 v248, v56, v180
	v_mov_b32_e32 v251, v168
	s_nop 1
	v_mov_b32_dpp v251, v144 row_shr:1 row_mask:0xf bank_mask:0xf
	v_fma_f32 v168, v164, v172, v152
	v_fma_f32 v164, v160, v251, v168
	v_fma_f32 v160, v248, v156, v164
	v_mul_f32_e32 v156, 0x3d922279, v160
	v_fmaak_f32 v164, v160, v156, 0x3fcc422a
	v_mul_f32_e32 v156, v160, v164
	v_mul_f32_e32 v164, 0xbfb8aa3b, v156
	v_exp_f32_e32 v156, v164
	s_nop 0
	v_add_f32_e32 v164, 1.0, v156
	v_rcp_f32_e32 v156, v164
	s_nop 0
	v_mul_f32_e32 v164, v160, v156
	v_mul_f32_e32 v156, v245, v164
	v_mul_f32_e32 v160, v25, v180
	v_mul_f32_e32 v164, v57, v181
	v_mov_b32_e32 v168, v169
	s_nop 1
	v_mov_b32_dpp v168, v145 row_shr:1 row_mask:0xf bank_mask:0xf
	v_mov_b32_e32 v169, v173
	s_nop 1
	v_mov_b32_dpp v169, v149 row_shr:1 row_mask:0xf bank_mask:0xf
	v_fma_f32 v245, v165, v169, v153
	v_fma_f32 v165, v161, v168, v245
	v_fma_f32 v161, v164, v157, v165
	v_mul_f32_e32 v157, 0x3d922279, v161
	v_fmaak_f32 v245, v161, v157, 0x3fcc422a
	v_mul_f32_e32 v157, v161, v245
	v_mul_f32_e32 v245, 0xbfb8aa3b, v157
	v_exp_f32_e32 v157, v245
	s_nop 0
	v_add_f32_e32 v245, 1.0, v157
	v_rcp_f32_e32 v157, v245
	s_nop 0
	v_mul_f32_e32 v245, v161, v157
	v_mul_f32_e32 v157, v160, v245
	v_cvt_pk_bf16_f32 v142, v156, v157
	v_pk_mul_f32 v[156:157], v[26:27], v[180:181] op_sel_hi:[1,0]
	v_mov_b32_e32 v160, v174
	v_mov_b32_e32 v161, v175
	s_nop 1
	v_mov_b32_dpp v160, v150 row_shr:1 row_mask:0xf bank_mask:0xf
	v_mov_b32_dpp v161, v151 row_shr:1 row_mask:0xf bank_mask:0xf
	v_pk_fma_f32 v[164:165], v[166:167], v[160:161], v[154:155]
	v_pk_fma_f32 v[154:155], v[162:163], v[178:179], v[164:165]
	v_pk_fma_f32 v[160:161], v[202:203], v[158:159], v[154:155]
	v_pk_mul_f32 v[154:155], s[36:37], v[160:161] op_sel_hi:[0,1]
	v_pk_fma_f32 v[158:159], v[160:161], v[154:155], s[38:39] op_sel_hi:[1,1,0]
	v_pk_mul_f32 v[154:155], v[160:161], v[158:159]
	v_pk_mul_f32 v[158:159], s[30:31], v[154:155] op_sel_hi:[0,1]
	v_exp_f32_e32 v154, v158
	v_exp_f32_e32 v155, v159
	s_nop 0
	v_pk_add_f32 v[158:159], s[6:7], v[154:155] op_sel_hi:[0,1]
	v_rcp_f32_e32 v154, v158
	v_rcp_f32_e32 v155, v159
	s_nop 0
	v_pk_mul_f32 v[158:159], v[160:161], v[154:155]
	v_pk_mul_f32 v[154:155], v[156:157], v[158:159]
	v_cvt_pk_bf16_f32 v143, v154, v155
	v_mov_b32_e32 v152, v206
	v_mov_b32_e32 v153, v207
	s_and_saveexec_b64 s[6:7], s[8:9]
	s_cbranch_execz .LBB0_460
	s_and_b64 vcc, exec, s[14:15]
	s_cbranch_vccnz .LBB0_455
	v_readlane_b32 s14, v249, 19
	s_add_u32 s14, s14, s55
	v_readlane_b32 s15, v249, 21
	s_addc_u32 s15, s15, s53
	s_mov_b64 s[16:17], -1
	s_cbranch_execz .LBB0_456
	s_branch .LBB0_458

; __global__ void __launch_bounds__(NWAVES * 64, 2) mk_fwd(Args args) {
	.amdhsa_kernel _Z6mk_fwd4Args
		.amdhsa_group_segment_fixed_size 0
		.amdhsa_private_segment_fixed_size 0
		.amdhsa_kernarg_size 472
		.amdhsa_user_sgpr_count 2
		.amdhsa_user_sgpr_dispatch_ptr 0
		.amdhsa_user_sgpr_queue_ptr 0
		.amdhsa_user_sgpr_kernarg_segment_ptr 1
		.amdhsa_user_sgpr_dispatch_id 0
		.amdhsa_user_sgpr_kernarg_preload_length 0
		.amdhsa_user_sgpr_kernarg_preload_offset 0
		.amdhsa_user_sgpr_private_segment_size 0
		.amdhsa_uses_dynamic_stack 0
		.amdhsa_enable_private_segment 0
		.amdhsa_system_sgpr_workgroup_id_x 1
		.amdhsa_system_sgpr_workgroup_id_y 0
		.amdhsa_system_sgpr_workgroup_id_z 0
		.amdhsa_system_sgpr_workgroup_info 0
		.amdhsa_system_vgpr_workitem_id 0
		.amdhsa_next_free_vgpr 256
		.amdhsa_next_free_sgpr 98
		.amdhsa_accum_offset 256
		.amdhsa_reserve_vcc 1
		.amdhsa_float_round_mode_32 0
		.amdhsa_float_round_mode_16_64 0
		.amdhsa_float_denorm_mode_32 3
		.amdhsa_float_denorm_mode_16_64 3
		.amdhsa_dx10_clamp 1
		.amdhsa_ieee_mode 1
		.amdhsa_fp16_overflow 0
		.amdhsa_tg_split 0
		.amdhsa_exception_fp_ieee_invalid_op 0
		.amdhsa_exception_fp_denorm_src 0
		.amdhsa_exception_fp_ieee_div_zero 0
		.amdhsa_exception_fp_ieee_overflow 0
		.amdhsa_exception_fp_ieee_underflow 0
		.amdhsa_exception_fp_ieee_inexact 0
		.amdhsa_exception_int_div_zero 0
	.end_amdhsa_kernel

; __global__ void __launch_bounds__(NWAVES * 64, 2) mk_fwd(Args args) {
amdhsa.kernels:
  - .agpr_count:     0
    .args:
      - .offset:         0
        .size:           216
        .value_kind:     by_value
      - .offset:         216
        .size:           4
        .value_kind:     hidden_block_count_x
      - .offset:         220
        .size:           4
        .value_kind:     hidden_block_count_y
      - .offset:         224
        .size:           4
        .value_kind:     hidden_block_count_z
      - .offset:         228
        .size:           2
        .value_kind:     hidden_group_size_x
      - .offset:         230
        .size:           2
        .value_kind:     hidden_group_size_y
      - .offset:         232
        .size:           2
        .value_kind:     hidden_group_size_z
      - .offset:         234
        .size:           2
        .value_kind:     hidden_remainder_x
      - .offset:         236
        .size:           2
        .value_kind:     hidden_remainder_y
      - .offset:         238
        .size:           2
        .value_kind:     hidden_remainder_z
      - .offset:         256
        .size:           8
        .value_kind:     hidden_global_offset_x
      - .offset:         264
        .size:           8
        .value_kind:     hidden_global_offset_y
      - .offset:         272
        .size:           8
        .value_kind:     hidden_global_offset_z
      - .offset:         280
        .size:           2
        .value_kind:     hidden_grid_dims
      - .offset:         336
        .size:           4
        .value_kind:     hidden_dynamic_lds_size
    .group_segment_fixed_size: 0
    .kernarg_segment_align: 8
    .kernarg_segment_size: 472
    .language:       OpenCL C
    .language_version:
      - 2
      - 0
    .max_flat_workgroup_size: 512
    .name:           _Z6mk_fwd4Args
    .private_segment_fixed_size: 0
    .sgpr_count:     104
    .sgpr_spill_count: 133
    .symbol:         _Z6mk_fwd4Args.kd
    .uniform_work_group_size: 1
    .uses_dynamic_stack: false
    .vgpr_count:     256
    .vgpr_spill_count: 0
    .wavefront_size: 64
